# v35 + L2G: LRU pass-2 output loop issues its four gate loads together (counted waits)
# baseline (speedup 1.0000x reference)
; #define LAS __attribute__((address_space(3)))
; __device__ __forceinline__ unsigned pk2(float lo, float hi) { return f2bf(lo) | (f2bf(hi) << 16); }
; __device__ __forceinline__ void lru_pass2_unit(int cu, const h2* AD, const float2* LCS, const bf16* LG, bf16* MIX, lds_t* lds, int tid) {
;     ...
;     { typedef _Float16 h8 __attribute__((ext_vector_type(8))); const int c8 = (tid & 31) * 8;
; #pragma unroll 4
;         for (int i = 0; i < 8; ++i) { const int r = (tid >> 5) + 16 * i; const h8 hf = *(const LAS h8*)(HS + r * 512 + c8), hb = *(const LAS h8*)(HS + r * 512 + 256 + c8);
;             const v4u g = *(const v4u*)(LG + (size_t)(m0 + r) * 256 + c8); v4u o;
; #pragma unroll
;             for (int e = 0; e < 4; ++e) o[e] = pk2(((float)hf[2 * e] + (float)hb[2 * e]) * bflo(g[e]), ((float)hf[2 * e + 1] + (float)hb[2 * e + 1]) * bfhi(g[e]));
;             *(v4u*)(MIX + (size_t)(m0 + r) * DM + 768 + c8) = o; } }
;     __syncthreads();
.LBB0_804:
	v_add_u32_e32 v146, s0, v50
	global_load_dwordx4 v[130:133], v[54:55], off
	v_add_u32_e32 v134, 16, v146
	v_ashrrev_i32_e32 v135, 31, v134
	v_lshlrev_b64 v[134:135], 9, v[134:135]
	v_lshl_add_u64 v[134:135], v[12:13], 0, v[134:135]
	global_load_dwordx4 v[134:137], v[134:135], off
	v_add_u32_e32 v138, 32, v146
	v_ashrrev_i32_e32 v139, 31, v138
	v_lshlrev_b64 v[138:139], 9, v[138:139]
	v_lshl_add_u64 v[138:139], v[12:13], 0, v[138:139]
	global_load_dwordx4 v[138:141], v[138:139], off
	v_add_u32_e32 v142, 48, v146
	v_ashrrev_i32_e32 v143, 31, v142
	v_lshlrev_b64 v[142:143], 9, v[142:143]
	v_lshl_add_u64 v[142:143], v[12:13], 0, v[142:143]
	global_load_dwordx4 v[142:145], v[142:143], off
	ds_read_b128 v[56:59], v0
	ds_read_b128 v[60:63], v0 offset:512
	v_lshl_add_u64 v[54:55], v[54:55], 0, s[66:67]
	s_waitcnt lgkmcnt(1)
	v_cvt_f32_f16_e32 v65, v57
	v_cvt_f32_f16_e32 v64, v56
	s_waitcnt lgkmcnt(0)
	v_cvt_f32_f16_e32 v67, v61
	v_cvt_f32_f16_e32 v66, v60
	v_cvt_f32_f16_sdwa v57, v57 dst_sel:DWORD dst_unused:UNUSED_PAD src0_sel:WORD_1
	v_cvt_f32_f16_sdwa v56, v56 dst_sel:DWORD dst_unused:UNUSED_PAD src0_sel:WORD_1
	v_cvt_f32_f16_sdwa v61, v61 dst_sel:DWORD dst_unused:UNUSED_PAD src0_sel:WORD_1
	v_cvt_f32_f16_sdwa v60, v60 dst_sel:DWORD dst_unused:UNUSED_PAD src0_sel:WORD_1
	v_pk_add_f32 v[64:65], v[64:65], v[66:67]
	v_pk_add_f32 v[56:57], v[56:57], v[60:61]
	v_cvt_f32_f16_e32 v61, v63
	v_cvt_f32_f16_e32 v60, v62
	s_waitcnt vmcnt(3)
	v_mov_b32_e32 v2, v130
	v_mov_b32_e32 v3, v131
	v_mov_b32_e32 v4, v132
	v_mov_b32_e32 v5, v133
	v_lshlrev_b32_e32 v67, 16, v3
	v_lshlrev_b32_e32 v66, 16, v2
	v_and_b32_e32 v3, 0xffff0000, v3
	v_and_b32_e32 v2, 0xffff0000, v2
	v_pk_mul_f32 v[2:3], v[56:57], v[2:3]
	v_cvt_f32_f16_e32 v57, v59
	v_cvt_f32_f16_e32 v56, v58
	v_cvt_f32_f16_sdwa v59, v59 dst_sel:DWORD dst_unused:UNUSED_PAD src0_sel:WORD_1
	v_cvt_f32_f16_sdwa v58, v58 dst_sel:DWORD dst_unused:UNUSED_PAD src0_sel:WORD_1
	v_pk_mul_f32 v[64:65], v[64:65], v[66:67]
	v_pk_add_f32 v[56:57], v[56:57], v[60:61]
	v_lshlrev_b32_e32 v61, 16, v5
	v_lshlrev_b32_e32 v60, 16, v4
	v_pk_mul_f32 v[56:57], v[56:57], v[60:61]
	v_cvt_f32_f16_sdwa v61, v63 dst_sel:DWORD dst_unused:UNUSED_PAD src0_sel:WORD_1
	v_cvt_f32_f16_sdwa v60, v62 dst_sel:DWORD dst_unused:UNUSED_PAD src0_sel:WORD_1
	v_and_b32_e32 v5, 0xffff0000, v5
	v_and_b32_e32 v4, 0xffff0000, v4
	v_bfe_u32 v23, v3, 16, 1
	v_pk_add_f32 v[58:59], v[58:59], v[60:61]
	v_bfe_u32 v25, v2, 16, 1
	v_pk_mul_f32 v[4:5], v[58:59], v[4:5]
	v_add3_u32 v2, v2, v25, s33
	v_bfe_u32 v19, v5, 16, 1
	v_add3_u32 v5, v5, v19, s33
	v_bfe_u32 v19, v64, 16, 1
	v_bfe_u32 v21, v4, 16, 1
	v_add3_u32 v19, v64, v19, s33
	v_add3_u32 v3, v3, v23, s33
	v_add3_u32 v4, v4, v21, s33
	v_bfe_u32 v21, v65, 16, 1
	v_bfe_u32 v23, v56, 16, 1
	v_bfe_u32 v25, v57, 16, 1
	v_lshrrev_b32_e32 v19, 16, v19
	v_add3_u32 v25, v57, v25, s33
	v_add3_u32 v23, v56, v23, s33
	v_add3_u32 v21, v65, v21, s33
	v_and_or_b32 v2, v2, s87, v19
	v_add_u32_e32 v19, s0, v50
	v_lshrrev_b32_e32 v21, 16, v21
	v_lshrrev_b32_e32 v23, 16, v23
	v_lshrrev_b32_e32 v25, 16, v25
	v_add_u32_e32 v64, 16, v19
	v_and_or_b32 v5, v5, s87, v25
	v_and_or_b32 v4, v4, s87, v23
	v_and_or_b32 v3, v3, s87, v21
	v_ashrrev_i32_e32 v65, 31, v64
	global_store_dwordx4 v[52:53], v[2:5], off
	ds_read_b128 v[56:59], v0 offset:16384
	ds_read_b128 v[60:63], v0 offset:16896
	v_lshlrev_b64 v[2:3], 9, v[64:65]
	v_lshl_add_u64 v[2:3], v[12:13], 0, v[2:3]
	s_waitcnt lgkmcnt(1)
	v_cvt_f32_f16_e32 v67, v57
	v_cvt_f32_f16_e32 v66, v56
	s_waitcnt lgkmcnt(0)
	v_cvt_f32_f16_e32 v69, v61
	v_cvt_f32_f16_e32 v68, v60
	v_cvt_f32_f16_sdwa v57, v57 dst_sel:DWORD dst_unused:UNUSED_PAD src0_sel:WORD_1
	v_cvt_f32_f16_sdwa v56, v56 dst_sel:DWORD dst_unused:UNUSED_PAD src0_sel:WORD_1
	v_cvt_f32_f16_sdwa v61, v61 dst_sel:DWORD dst_unused:UNUSED_PAD src0_sel:WORD_1
	v_cvt_f32_f16_sdwa v60, v60 dst_sel:DWORD dst_unused:UNUSED_PAD src0_sel:WORD_1
	v_pk_add_f32 v[66:67], v[66:67], v[68:69]
	s_add_i32 s0, s0, 64
	v_lshl_add_u64 v[52:53], v[52:53], 0, s[96:97]
	v_pk_add_f32 v[56:57], v[56:57], v[60:61]
	v_cvt_f32_f16_e32 v61, v63
	v_cvt_f32_f16_e32 v60, v62
	s_cmpk_lg_i32 s0, 0x80
	s_waitcnt vmcnt(3)
	v_mov_b32_e32 v2, v134
	v_mov_b32_e32 v3, v135
	v_mov_b32_e32 v4, v136
	v_mov_b32_e32 v5, v137
	v_lshlrev_b32_e32 v69, 16, v3
	v_lshlrev_b32_e32 v68, 16, v2
	v_and_b32_e32 v3, 0xffff0000, v3
	v_and_b32_e32 v2, 0xffff0000, v2
	v_pk_mul_f32 v[2:3], v[56:57], v[2:3]
	v_cvt_f32_f16_e32 v57, v59
	v_cvt_f32_f16_e32 v56, v58
	v_cvt_f32_f16_sdwa v59, v59 dst_sel:DWORD dst_unused:UNUSED_PAD src0_sel:WORD_1
	v_cvt_f32_f16_sdwa v58, v58 dst_sel:DWORD dst_unused:UNUSED_PAD src0_sel:WORD_1
	v_pk_mul_f32 v[66:67], v[66:67], v[68:69]
	v_pk_add_f32 v[56:57], v[56:57], v[60:61]
	v_lshlrev_b32_e32 v61, 16, v5
	v_lshlrev_b32_e32 v60, 16, v4
	v_pk_mul_f32 v[56:57], v[56:57], v[60:61]
	v_cvt_f32_f16_sdwa v61, v63 dst_sel:DWORD dst_unused:UNUSED_PAD src0_sel:WORD_1
	v_cvt_f32_f16_sdwa v60, v62 dst_sel:DWORD dst_unused:UNUSED_PAD src0_sel:WORD_1
	v_and_b32_e32 v5, 0xffff0000, v5
	v_and_b32_e32 v4, 0xffff0000, v4
	v_bfe_u32 v25, v3, 16, 1
	v_pk_add_f32 v[58:59], v[58:59], v[60:61]
	v_bfe_u32 v27, v2, 16, 1
	v_pk_mul_f32 v[4:5], v[58:59], v[4:5]
	v_add3_u32 v2, v2, v27, s33
	v_bfe_u32 v21, v5, 16, 1
	v_bfe_u32 v23, v4, 16, 1
	v_add3_u32 v3, v3, v25, s33
	v_add3_u32 v4, v4, v23, s33
	v_add3_u32 v5, v5, v21, s33
	v_bfe_u32 v21, v66, 16, 1
	v_bfe_u32 v23, v67, 16, 1
	v_bfe_u32 v25, v56, 16, 1
	v_bfe_u32 v27, v57, 16, 1
	v_add3_u32 v27, v57, v27, s33
	v_add3_u32 v25, v56, v25, s33
	v_add3_u32 v23, v67, v23, s33
	v_add3_u32 v21, v66, v21, s33
	v_lshrrev_b32_e32 v21, 16, v21
	v_lshrrev_b32_e32 v23, 16, v23
	v_lshrrev_b32_e32 v25, 16, v25
	v_lshrrev_b32_e32 v27, 16, v27
	v_lshlrev_b64 v[56:57], 11, v[64:65]
	v_and_or_b32 v5, v5, s87, v27
	v_and_or_b32 v4, v4, s87, v25
	v_and_or_b32 v3, v3, s87, v23
	v_and_or_b32 v2, v2, s87, v21
	v_lshl_add_u64 v[56:57], v[14:15], 0, v[56:57]
	global_store_dwordx4 v[56:57], v[2:5], off offset:1536
	v_add_u32_e32 v56, 32, v19
	v_ashrrev_i32_e32 v57, 31, v56
	v_lshlrev_b64 v[2:3], 9, v[56:57]
	v_lshl_add_u64 v[2:3], v[12:13], 0, v[2:3]
	ds_read_b128 v[58:61], v0 offset:32768
	ds_read_b128 v[62:65], v0 offset:33280
	v_lshlrev_b64 v[56:57], 11, v[56:57]
	v_lshl_add_u64 v[56:57], v[14:15], 0, v[56:57]
	s_waitcnt lgkmcnt(1)
; #define LAS __attribute__((address_space(3)))
; __device__ __forceinline__ unsigned pk2(float lo, float hi) { return f2bf(lo) | (f2bf(hi) << 16); }
; __device__ __forceinline__ void lru_pass2_unit(int cu, const h2* AD, const float2* LCS, const bf16* LG, bf16* MIX, lds_t* lds, int tid) {
;     ...
;     { typedef _Float16 h8 __attribute__((ext_vector_type(8))); const int c8 = (tid & 31) * 8;
; #pragma unroll 4
;         for (int i = 0; i < 8; ++i) { const int r = (tid >> 5) + 16 * i; const h8 hf = *(const LAS h8*)(HS + r * 512 + c8), hb = *(const LAS h8*)(HS + r * 512 + 256 + c8);
;             const v4u g = *(const v4u*)(LG + (size_t)(m0 + r) * 256 + c8); v4u o;
; #pragma unroll
;             for (int e = 0; e < 4; ++e) o[e] = pk2(((float)hf[2 * e] + (float)hb[2 * e]) * bflo(g[e]), ((float)hf[2 * e + 1] + (float)hb[2 * e + 1]) * bfhi(g[e]));
;             *(v4u*)(MIX + (size_t)(m0 + r) * DM + 768 + c8) = o; } }
;     __syncthreads();
	v_cvt_f32_f16_e32 v67, v59
	v_cvt_f32_f16_e32 v66, v58
	s_waitcnt lgkmcnt(0)
	v_cvt_f32_f16_e32 v69, v63
	v_cvt_f32_f16_e32 v68, v62
	v_cvt_f32_f16_sdwa v59, v59 dst_sel:DWORD dst_unused:UNUSED_PAD src0_sel:WORD_1
	v_cvt_f32_f16_sdwa v58, v58 dst_sel:DWORD dst_unused:UNUSED_PAD src0_sel:WORD_1
	v_cvt_f32_f16_sdwa v63, v63 dst_sel:DWORD dst_unused:UNUSED_PAD src0_sel:WORD_1
	v_cvt_f32_f16_sdwa v62, v62 dst_sel:DWORD dst_unused:UNUSED_PAD src0_sel:WORD_1
	v_pk_add_f32 v[66:67], v[66:67], v[68:69]
	v_pk_add_f32 v[58:59], v[58:59], v[62:63]
	v_cvt_f32_f16_e32 v63, v65
	v_cvt_f32_f16_e32 v62, v64
	s_waitcnt vmcnt(3)
	v_mov_b32_e32 v2, v138
	v_mov_b32_e32 v3, v139
	v_mov_b32_e32 v4, v140
	v_mov_b32_e32 v5, v141
	v_lshlrev_b32_e32 v69, 16, v3
	v_lshlrev_b32_e32 v68, 16, v2
	v_and_b32_e32 v3, 0xffff0000, v3
	v_and_b32_e32 v2, 0xffff0000, v2
	v_pk_mul_f32 v[2:3], v[58:59], v[2:3]
	v_cvt_f32_f16_e32 v59, v61
	v_cvt_f32_f16_e32 v58, v60
	v_cvt_f32_f16_sdwa v61, v61 dst_sel:DWORD dst_unused:UNUSED_PAD src0_sel:WORD_1
	v_cvt_f32_f16_sdwa v60, v60 dst_sel:DWORD dst_unused:UNUSED_PAD src0_sel:WORD_1
	v_pk_mul_f32 v[66:67], v[66:67], v[68:69]
	v_pk_add_f32 v[58:59], v[58:59], v[62:63]
	v_lshlrev_b32_e32 v63, 16, v5
	v_lshlrev_b32_e32 v62, 16, v4
	v_pk_mul_f32 v[58:59], v[58:59], v[62:63]
	v_cvt_f32_f16_sdwa v63, v65 dst_sel:DWORD dst_unused:UNUSED_PAD src0_sel:WORD_1
	v_cvt_f32_f16_sdwa v62, v64 dst_sel:DWORD dst_unused:UNUSED_PAD src0_sel:WORD_1
	v_and_b32_e32 v5, 0xffff0000, v5
	v_and_b32_e32 v4, 0xffff0000, v4
	v_bfe_u32 v25, v3, 16, 1
	v_pk_add_f32 v[60:61], v[60:61], v[62:63]
	v_bfe_u32 v27, v2, 16, 1
	v_pk_mul_f32 v[4:5], v[60:61], v[4:5]
	v_add3_u32 v2, v2, v27, s33
	v_bfe_u32 v21, v5, 16, 1
	v_bfe_u32 v23, v4, 16, 1
	v_add3_u32 v3, v3, v25, s33
	v_add3_u32 v4, v4, v23, s33
	v_add3_u32 v5, v5, v21, s33
	v_bfe_u32 v21, v66, 16, 1
	v_bfe_u32 v23, v67, 16, 1
	v_bfe_u32 v25, v58, 16, 1
	v_bfe_u32 v27, v59, 16, 1
	v_add3_u32 v27, v59, v27, s33
	v_add3_u32 v25, v58, v25, s33
	v_add3_u32 v23, v67, v23, s33
	v_add3_u32 v21, v66, v21, s33
	v_lshrrev_b32_e32 v21, 16, v21
	v_lshrrev_b32_e32 v23, 16, v23
	v_lshrrev_b32_e32 v25, 16, v25
	v_lshrrev_b32_e32 v27, 16, v27
	v_and_or_b32 v5, v5, s87, v27
	v_and_or_b32 v4, v4, s87, v25
	v_and_or_b32 v3, v3, s87, v23
	v_and_or_b32 v2, v2, s87, v21
	global_store_dwordx4 v[56:57], v[2:5], off offset:1536
	ds_read_b128 v[60:63], v0 offset:49152
	ds_read_b128 v[64:67], v0 offset:49664
	v_add_u32_e32 v2, 48, v19
	v_ashrrev_i32_e32 v3, 31, v2
	v_lshlrev_b64 v[4:5], 9, v[2:3]
	v_lshl_add_u64 v[4:5], v[12:13], 0, v[4:5]
	s_waitcnt lgkmcnt(1)
	v_cvt_f32_f16_e32 v5, v61
	v_cvt_f32_f16_e32 v4, v60
	s_waitcnt lgkmcnt(0)
	v_cvt_f32_f16_e32 v69, v65
	v_cvt_f32_f16_e32 v68, v64
	v_cvt_f32_f16_sdwa v61, v61 dst_sel:DWORD dst_unused:UNUSED_PAD src0_sel:WORD_1
	v_cvt_f32_f16_sdwa v60, v60 dst_sel:DWORD dst_unused:UNUSED_PAD src0_sel:WORD_1
	v_cvt_f32_f16_sdwa v65, v65 dst_sel:DWORD dst_unused:UNUSED_PAD src0_sel:WORD_1
	v_cvt_f32_f16_sdwa v64, v64 dst_sel:DWORD dst_unused:UNUSED_PAD src0_sel:WORD_1
	v_pk_add_f32 v[4:5], v[4:5], v[68:69]
	v_lshlrev_b64 v[2:3], 11, v[2:3]
	v_lshl_add_u64 v[2:3], v[14:15], 0, v[2:3]
	v_pk_add_f32 v[60:61], v[60:61], v[64:65]
	v_cvt_f32_f16_e32 v65, v67
	v_cvt_f32_f16_e32 v64, v66
	v_add_u32_e32 v0, 0x10000, v0
	s_waitcnt vmcnt(3)
	v_mov_b32_e32 v56, v142
	v_mov_b32_e32 v57, v143
	v_mov_b32_e32 v58, v144
	v_mov_b32_e32 v59, v145
	v_lshlrev_b32_e32 v69, 16, v57
	v_lshlrev_b32_e32 v68, 16, v56
	v_and_b32_e32 v57, 0xffff0000, v57
	v_and_b32_e32 v56, 0xffff0000, v56
	v_pk_mul_f32 v[56:57], v[60:61], v[56:57]
	v_cvt_f32_f16_e32 v61, v63
	v_cvt_f32_f16_e32 v60, v62
	v_cvt_f32_f16_sdwa v63, v63 dst_sel:DWORD dst_unused:UNUSED_PAD src0_sel:WORD_1
	v_cvt_f32_f16_sdwa v62, v62 dst_sel:DWORD dst_unused:UNUSED_PAD src0_sel:WORD_1
	v_pk_mul_f32 v[4:5], v[4:5], v[68:69]
	v_pk_add_f32 v[60:61], v[60:61], v[64:65]
	v_lshlrev_b32_e32 v65, 16, v59
	v_lshlrev_b32_e32 v64, 16, v58
	v_pk_mul_f32 v[60:61], v[60:61], v[64:65]
	v_cvt_f32_f16_sdwa v65, v67 dst_sel:DWORD dst_unused:UNUSED_PAD src0_sel:WORD_1
	v_cvt_f32_f16_sdwa v64, v66 dst_sel:DWORD dst_unused:UNUSED_PAD src0_sel:WORD_1
	v_and_b32_e32 v59, 0xffff0000, v59
	v_and_b32_e32 v58, 0xffff0000, v58
	v_bfe_u32 v27, v4, 16, 1
	v_pk_add_f32 v[62:63], v[62:63], v[64:65]
	v_bfe_u32 v29, v5, 16, 1
	v_pk_mul_f32 v[58:59], v[62:63], v[58:59]
	v_bfe_u32 v31, v60, 16, 1
	v_bfe_u32 v33, v61, 16, 1
	v_bfe_u32 v19, v59, 16, 1
	v_bfe_u32 v21, v58, 16, 1
	v_bfe_u32 v23, v57, 16, 1
	v_bfe_u32 v25, v56, 16, 1
	v_add3_u32 v33, v61, v33, s33
	v_add3_u32 v31, v60, v31, s33
	v_add3_u32 v5, v5, v29, s33
	v_add3_u32 v4, v4, v27, s33
	v_add3_u32 v25, v56, v25, s33
	v_add3_u32 v23, v57, v23, s33
	v_add3_u32 v21, v58, v21, s33
	v_add3_u32 v19, v59, v19, s33
	v_lshrrev_b32_e32 v4, 16, v4
	v_lshrrev_b32_e32 v5, 16, v5
	v_lshrrev_b32_e32 v27, 16, v31
	v_lshrrev_b32_e32 v29, 16, v33
	v_and_or_b32 v59, v19, s87, v29
	v_and_or_b32 v58, v21, s87, v27
	v_and_or_b32 v57, v23, s87, v5
	v_and_or_b32 v56, v25, s87, v4
	global_store_dwordx4 v[2:3], v[56:59], off offset:1536
	s_cbranch_scc1 .LBB0_804
	s_barrier
	s_branch .LBB0_786
